# v13: v9 plus nt stores for the final f32 output rows
# speedup vs baseline: 1.0123x; 1.0123x over previous
.LBB0_2878:
	v_mov_b32_e32 v80, v71
	v_mov_b32_e32 v81, v68
	v_mov_b32_e32 v82, v70
	v_mov_b32_e32 v83, v69
	v_pk_add_f32 v[80:81], v[80:81], v[82:83]
	v_mov_b32_e32 v82, v67
	v_mov_b32_e32 v83, v62
	v_mov_b32_e32 v84, v66
	v_mov_b32_e32 v85, v63
	v_pk_add_f32 v[82:83], v[82:83], v[84:85]
	v_add_f32_e32 v32, v80, v81
	v_pk_add_f32 v[82:83], v[82:83], v[82:83] op_sel_hi:[0,1]
	v_add_f32_e32 v81, 0, v32
	v_add_f32_e32 v85, v64, v65
	v_add_f32_e32 v87, v60, v61
	v_mov_b32_e32 v84, v58
	v_mov_b32_e32 v86, v59
	v_mov_b32_e32 v82, v72
	v_mov_b32_e32 v80, v73
	v_pk_add_f32 v[84:85], v[84:85], v[86:87]
	v_pk_add_f32 v[80:81], v[82:83], v[80:81]
	s_ashr_i32 s69, s68, 31
	v_pk_add_f32 v[80:81], v[84:85], v[80:81]
	s_nop 0
	v_add_f32_e32 v32, v80, v81
	s_nop 1
	v_add_f32_dpp v32, v32, v32 quad_perm:[1,0,3,2] row_mask:0xf bank_mask:0xf bound_ctrl:1
	s_nop 1
	v_add_f32_dpp v32, v32, v32 quad_perm:[2,3,0,1] row_mask:0xf bank_mask:0xf bound_ctrl:1
	s_nop 1
	v_add_f32_dpp v32, v32, v32 row_half_mirror row_mask:0xf bank_mask:0xf bound_ctrl:1
	s_nop 1
	v_add_f32_dpp v32, v32, v32 row_mirror row_mask:0xf bank_mask:0xf bound_ctrl:1
	s_nop 0
	v_readlane_b32 s11, v32, 16
	v_readlane_b32 s12, v32, 48
	v_readlane_b32 s2, v32, 0
	v_readlane_b32 s3, v32, 32
	v_mov_b32_e32 v80, s11
	v_mov_b32_e32 v81, s12
	v_pk_add_f32 v[80:81], s[2:3], v[80:81]
	s_nop 0
	v_add_f32_e32 v79, v80, v81
	v_fmac_f32_e32 v71, 0xba800000, v79
	v_fmac_f32_e32 v70, 0xba800000, v79
	v_fmac_f32_e32 v69, 0xba800000, v79
	v_fmac_f32_e32 v68, 0xba800000, v79
	v_pk_mul_f32 v[80:81], v[68:69], v[68:69]
	v_pk_mul_f32 v[82:83], v[70:71], v[70:71]
	v_fmac_f32_e32 v67, 0xba800000, v79
	v_pk_mov_b32 v[84:85], v[82:83], v[80:81] op_sel:[1,0]
	v_mov_b32_e32 v83, v81
	v_fmac_f32_e32 v66, 0xba800000, v79
	v_fmac_f32_e32 v63, 0xba800000, v79
	v_fmac_f32_e32 v62, 0xba800000, v79
	v_pk_add_f32 v[80:81], v[84:85], v[82:83]
	v_pk_mul_f32 v[82:83], v[62:63], v[62:63]
	v_pk_mul_f32 v[84:85], v[66:67], v[66:67]
	v_fmac_f32_e32 v64, 0xba800000, v79
	v_pk_mov_b32 v[86:87], v[84:85], v[82:83] op_sel:[1,0]
	v_mov_b32_e32 v85, v83
	v_fmac_f32_e32 v65, 0xba800000, v79
	v_fmac_f32_e32 v60, 0xba800000, v79
	v_mul_f32_e32 v32, v64, v64
	v_pk_add_f32 v[82:83], v[86:87], v[84:85]
	v_fmac_f32_e32 v61, 0xba800000, v79
	v_pk_fma_f32 v[84:85], v[64:65], v[64:65], v[32:33] op_sel_hi:[1,1,0]
	v_mul_f32_e32 v32, v60, v60
	v_pk_add_f32 v[80:81], v[80:81], v[80:81] op_sel_hi:[0,1]
	v_pk_add_f32 v[82:83], v[82:83], v[82:83] op_sel_hi:[0,1]
	v_pk_fma_f32 v[86:87], v[60:61], v[60:61], v[32:33] op_sel_hi:[1,1,0]
	v_fmamk_f32 v73, v79, 0xba800000, v73
	v_fmamk_f32 v72, v79, 0xba800000, v72
	v_fmamk_f32 v59, v79, 0xba800000, v59
	v_fmac_f32_e32 v58, 0xba800000, v79
	v_mul_f32_e32 v84, v58, v58
	v_mul_f32_e32 v86, v59, v59
	v_mul_f32_e32 v80, v72, v72
	v_mul_f32_e32 v82, v73, v73
	v_pk_add_f32 v[84:85], v[84:85], v[86:87]
	v_pk_add_f32 v[80:81], v[80:81], v[82:83]
	s_nop 0
	v_pk_add_f32 v[80:81], v[84:85], v[80:81]
	s_nop 0
	v_add_f32_e32 v32, v80, v81
	s_nop 1
	v_add_f32_dpp v32, v32, v32 quad_perm:[1,0,3,2] row_mask:0xf bank_mask:0xf bound_ctrl:1
	s_nop 1
	v_add_f32_dpp v32, v32, v32 quad_perm:[2,3,0,1] row_mask:0xf bank_mask:0xf bound_ctrl:1
	s_nop 1
	v_add_f32_dpp v32, v32, v32 row_half_mirror row_mask:0xf bank_mask:0xf bound_ctrl:1
	s_nop 1
	v_add_f32_dpp v32, v32, v32 row_mirror row_mask:0xf bank_mask:0xf bound_ctrl:1
	s_nop 0
	v_readlane_b32 s11, v32, 16
	v_readlane_b32 s12, v32, 48
	v_readlane_b32 s2, v32, 0
	v_readlane_b32 s3, v32, 32
	v_mov_b32_e32 v80, s11
	v_mov_b32_e32 v81, s12
	v_pk_add_f32 v[80:81], s[2:3], v[80:81]
	s_nop 0
	v_add_f32_e32 v32, v80, v81
	v_fmamk_f32 v32, v32, 0x3a800000, v74
	v_mul_f32_e32 v79, 0x4f800000, v32
	v_cmp_gt_f32_e32 vcc, s17, v32
	s_nop 1
	v_cndmask_b32_e32 v32, v32, v79, vcc
	v_sqrt_f32_e32 v79, v32
	s_nop 0
	v_add_u32_e32 v80, -1, v79
	v_fma_f32 v81, -v80, v79, v32
	v_cmp_ge_f32_e64 s[2:3], 0, v81
	v_add_u32_e32 v81, 1, v79
	s_nop 0
	v_cndmask_b32_e64 v80, v79, v80, s[2:3]
	v_fma_f32 v79, -v81, v79, v32
	v_cmp_lt_f32_e64 s[2:3], 0, v79
	s_nop 1
	v_cndmask_b32_e64 v79, v80, v81, s[2:3]
	v_mul_f32_e32 v80, 0x37800000, v79
	v_cndmask_b32_e32 v79, v79, v80, vcc
	v_cmp_class_f32_e32 vcc, v32, v75
	s_nop 1
	v_cndmask_b32_e32 v32, v79, v32, vcc
	v_div_scale_f32 v79, s[2:3], v32, v32, 1.0
	v_rcp_f32_e32 v80, v79
	s_lshl_b64 s[2:3], s[68:69], 12
	s_sub_i32 s68, s10, s33
	s_cmp_gt_i32 s68, 0xffff
	v_fma_f32 v81, -v79, v80, 1.0
	v_fmac_f32_e32 v80, v81, v80
	v_div_scale_f32 v81, vcc, 1.0, v32, 1.0
	v_mul_f32_e32 v82, v81, v80
	v_fma_f32 v83, -v79, v82, v81
	v_fmac_f32_e32 v82, v83, v80
	v_fma_f32 v79, -v79, v82, v81
	v_div_fmas_f32 v79, v79, v80, v82
	v_div_fixup_f32 v32, v79, v32, 1.0
	v_pk_mul_f32 v[80:81], v[70:71], v[32:33] op_sel_hi:[1,0]
	v_pk_mul_f32 v[68:69], v[68:69], v[32:33] op_sel_hi:[1,0]
	v_pk_mul_f32 v[62:63], v[62:63], v[32:33] op_sel_hi:[1,0]
	v_pk_fma_f32 v[70:71], v[2:3], v[68:69], v[6:7]
	v_pk_fma_f32 v[68:69], v[0:1], v[80:81], v[4:5]
	v_lshl_add_u64 v[80:81], v[48:49], 0, s[2:3]
	v_pk_mul_f32 v[64:65], v[64:65], v[32:33] op_sel_hi:[1,0]
	v_pk_mul_f32 v[60:61], v[60:61], v[32:33] op_sel_hi:[1,0]
	flat_store_dwordx4 v[80:81], v[68:71] nt
	v_pk_mul_f32 v[66:67], v[66:67], v[32:33] op_sel_hi:[1,0]
	v_pk_mul_f32 v[58:59], v[58:59], v[32:33] op_sel_hi:[1,0]
	v_pk_fma_f32 v[68:69], v[10:11], v[62:63], v[18:19]
	v_pk_fma_f32 v[62:63], v[14:15], v[60:61], v[22:23]
	v_pk_fma_f32 v[60:61], v[12:13], v[64:65], v[20:21]
	flat_store_dwordx4 v[80:81], v[60:63] offset:2048 nt
	v_pk_fma_f32 v[66:67], v[8:9], v[66:67], v[16:17]
	v_pk_fma_f32 v[58:59], v[24:25], v[58:59], v[28:29]
	v_pk_mul_f32 v[60:61], v[72:73], v[32:33] op_sel_hi:[1,0]
	flat_store_dwordx4 v[80:81], v[66:69] offset:1024 nt
	v_pk_fma_f32 v[60:61], v[26:27], v[60:61], v[30:31]
	flat_store_dwordx4 v[80:81], v[58:61] offset:3072 nt
	v_mov_b32_e32 v64, v42
	v_mov_b32_e32 v65, v43
	v_mov_b32_e32 v62, v40
	v_mov_b32_e32 v63, v41
	v_mov_b32_e32 v60, v36
	v_mov_b32_e32 v61, v37
	v_mov_b32_e32 v58, v34
	v_mov_b32_e32 v59, v35
	s_waitcnt vmcnt(0) lgkmcnt(0)
	v_mov_b64_e32 v[34:35], v[50:51]
	v_mov_b64_e32 v[36:37], v[52:53]
	v_mov_b64_e32 v[40:41], v[54:55]
	v_mov_b64_e32 v[42:43], v[56:57]
	v_mov_b32_e32 v79, v39
	v_mov_b32_e32 v39, v77
	v_mov_b32_e32 v80, v33
	v_mov_b32_e32 v33, v78
	s_cbranch_scc1 .LBB0_2888
